# mix2 ssd_inter: 16 start-state fragment loads per (head,dir) pass issued together with counted vmcnt instead of load-wait-mfma ladders (both latent and context variants); plus earlier GEMM/epilogue/mi
# speedup vs baseline: 1.1104x; 1.0014x over previous
.LBB0_45:
	s_xor_b64 s[6:7], s[4:5], -1
	s_mov_b64 s[4:5], 0
	s_and_b64 vcc, exec, s[6:7]
	v_lshl_add_u32 v64, s12, 7, v139
	v_add_u32_e32 v64, 0xc400, v64
	ds_read2_b32 v[64:65], v64 offset1:16
	s_mov_b32 s12, 1
	s_waitcnt lgkmcnt(0)
	v_pk_fma_f32 v[124:125], v[36:37], v[64:65], v[124:125] op_sel_hi:[1,0,1]
	v_mov_b32_e32 v36, v65
	v_pk_fma_f32 v[108:109], v[32:33], v[36:37], v[108:109] op_sel_hi:[1,0,1]
	v_pk_fma_f32 v[122:123], v[38:39], v[64:65], v[122:123] op_sel_hi:[1,0,1]
	v_pk_fma_f32 v[106:107], v[34:35], v[36:37], v[106:107] op_sel_hi:[1,0,1]
	v_pk_fma_f32 v[120:121], v[56:57], v[64:65], v[120:121] op_sel_hi:[1,0,1]
	v_pk_fma_f32 v[104:105], v[60:61], v[36:37], v[104:105] op_sel_hi:[1,0,1]
	v_pk_fma_f32 v[118:119], v[58:59], v[64:65], v[118:119] op_sel_hi:[1,0,1]
	v_pk_fma_f32 v[102:103], v[62:63], v[36:37], v[102:103] op_sel_hi:[1,0,1]
	v_pk_fma_f32 v[116:117], v[40:41], v[64:65], v[116:117] op_sel_hi:[1,0,1]
	v_pk_fma_f32 v[100:101], v[44:45], v[36:37], v[100:101] op_sel_hi:[1,0,1]
	v_pk_fma_f32 v[114:115], v[42:43], v[64:65], v[114:115] op_sel_hi:[1,0,1]
	v_pk_fma_f32 v[98:99], v[46:47], v[36:37], v[98:99] op_sel_hi:[1,0,1]
	v_pk_fma_f32 v[112:113], v[48:49], v[64:65], v[112:113] op_sel_hi:[1,0,1]
	v_pk_fma_f32 v[96:97], v[52:53], v[36:37], v[96:97] op_sel_hi:[1,0,1]
	v_pk_fma_f32 v[110:111], v[50:51], v[64:65], v[110:111] op_sel_hi:[1,0,1]
	v_pk_fma_f32 v[94:95], v[54:55], v[36:37], v[94:95] op_sel_hi:[1,0,1]
	s_cbranch_vccnz .LBB0_42
.LBB0_46:
	v_lshl_add_u32 v32, s12, 3, v138
	v_ashrrev_i32_e32 v33, 31, v32
	s_cmp_lg_u32 s10, s12
	v_lshlrev_b64 v[32:33], 15, v[32:33]
	s_cselect_b64 s[6:7], -1, 0
	s_lshl_b32 s0, s12, 14
	v_lshl_add_u64 v[32:33], s[30:31], 0, v[32:33]
	s_cmp_eq_u32 s10, s12
	v_lshl_add_u64 v[126:127], v[32:33], 0, s[0:1]
	s_cbranch_scc1 .Lm2c_zero
	v_lshl_add_u64 v[150:151], v[126:127], 0, v[168:169]
	v_mov_b32_e32 v91, v169
	v_lshl_add_u64 v[150:151], v[150:151], 0, v[90:91]
	v_lshl_add_u64 v[144:145], v[150:151], 0, s[34:35]
	v_lshl_add_u64 v[146:147], v[150:151], 0, s[26:27]
	v_lshl_add_u64 v[148:149], v[150:151], 0, s[86:87]
	global_load_dwordx4 v[176:179], v[150:151], off
	global_load_dwordx4 v[180:183], v[144:145], off
	global_load_dwordx4 v[184:187], v[146:147], off
	global_load_dwordx4 v[188:191], v[148:149], off
	global_load_dwordx4 v[192:195], v[150:151], off offset:64
	global_load_dwordx4 v[196:199], v[144:145], off offset:64
	global_load_dwordx4 v[200:203], v[146:147], off offset:64
	global_load_dwordx4 v[204:207], v[148:149], off offset:64
	global_load_dwordx4 v[222:225], v[150:151], off offset:128
	global_load_dwordx4 v[226:229], v[144:145], off offset:128
	global_load_dwordx4 v[230:233], v[146:147], off offset:128
	global_load_dwordx4 v[234:237], v[148:149], off offset:128
	global_load_dwordx4 v[238:241], v[150:151], off offset:192
	global_load_dwordx4 v[242:245], v[144:145], off offset:192
	global_load_dwordx4 v[246:249], v[146:147], off offset:192
	global_load_dwordx4 v[152:155], v[148:149], off offset:192
	s_waitcnt lgkmcnt(0)
	s_waitcnt vmcnt(15)
	v_mfma_f32_16x16x32_f16 v[36:39], v[176:179], v[0:3], 0
	v_mfma_f32_16x16x32_f16 v[32:35], v[176:179], v[8:11], 0
	s_waitcnt vmcnt(14)
	v_mfma_f32_16x16x32_f16 v[56:59], v[180:183], v[0:3], 0
	v_mfma_f32_16x16x32_f16 v[60:63], v[180:183], v[8:11], 0
	s_waitcnt vmcnt(13)
	v_mfma_f32_16x16x32_f16 v[40:43], v[184:187], v[0:3], 0
	v_mfma_f32_16x16x32_f16 v[44:47], v[184:187], v[8:11], 0
	s_waitcnt vmcnt(12)
	v_mfma_f32_16x16x32_f16 v[48:51], v[188:191], v[0:3], 0
	v_mfma_f32_16x16x32_f16 v[52:55], v[188:191], v[8:11], 0
	s_waitcnt vmcnt(11)
	v_mfma_f32_16x16x32_f16 v[36:39], v[192:195], v[4:7], v[36:39]
	v_mfma_f32_16x16x32_f16 v[32:35], v[192:195], v[12:15], v[32:35]
	s_waitcnt vmcnt(10)
	v_mfma_f32_16x16x32_f16 v[56:59], v[196:199], v[4:7], v[56:59]
	v_mfma_f32_16x16x32_f16 v[60:63], v[196:199], v[12:15], v[60:63]
	s_waitcnt vmcnt(9)
	v_mfma_f32_16x16x32_f16 v[40:43], v[200:203], v[4:7], v[40:43]
	v_mfma_f32_16x16x32_f16 v[44:47], v[200:203], v[12:15], v[44:47]
	s_waitcnt vmcnt(8)
	v_mfma_f32_16x16x32_f16 v[48:51], v[204:207], v[4:7], v[48:51]
	v_mfma_f32_16x16x32_f16 v[52:55], v[204:207], v[12:15], v[52:55]
	s_waitcnt vmcnt(7)
	v_mfma_f32_16x16x32_f16 v[36:39], v[222:225], v[16:19], v[36:39]
	v_mfma_f32_16x16x32_f16 v[32:35], v[222:225], v[24:27], v[32:35]
	s_waitcnt vmcnt(6)
	v_mfma_f32_16x16x32_f16 v[56:59], v[226:229], v[16:19], v[56:59]
	v_mfma_f32_16x16x32_f16 v[60:63], v[226:229], v[24:27], v[60:63]
	s_waitcnt vmcnt(5)
	v_mfma_f32_16x16x32_f16 v[40:43], v[230:233], v[16:19], v[40:43]
	v_mfma_f32_16x16x32_f16 v[44:47], v[230:233], v[24:27], v[44:47]
	s_waitcnt vmcnt(4)
	v_mfma_f32_16x16x32_f16 v[48:51], v[234:237], v[16:19], v[48:51]
	v_mfma_f32_16x16x32_f16 v[52:55], v[234:237], v[24:27], v[52:55]
	s_waitcnt vmcnt(3)
	v_mfma_f32_16x16x32_f16 v[36:39], v[238:241], v[20:23], v[36:39]
	v_mfma_f32_16x16x32_f16 v[32:35], v[238:241], v[28:31], v[32:35]
	s_waitcnt vmcnt(2)
	v_mfma_f32_16x16x32_f16 v[56:59], v[242:245], v[20:23], v[56:59]
	v_mfma_f32_16x16x32_f16 v[60:63], v[242:245], v[28:31], v[60:63]
	s_waitcnt vmcnt(1)
	v_mfma_f32_16x16x32_f16 v[40:43], v[246:249], v[20:23], v[40:43]
	v_mfma_f32_16x16x32_f16 v[44:47], v[246:249], v[28:31], v[44:47]
	s_waitcnt vmcnt(0)
	v_mfma_f32_16x16x32_f16 v[48:51], v[152:155], v[20:23], v[48:51]
	v_mfma_f32_16x16x32_f16 v[52:55], v[152:155], v[28:31], v[52:55]
	s_nop 7
	s_branch .LBB0_45
.Lm2c_zero:
	v_mov_b32_e32 v36, 0
	v_mov_b32_e32 v37, 0
	v_mov_b32_e32 v38, 0
	v_mov_b32_e32 v39, 0
	v_mov_b32_e32 v32, 0
	v_mov_b32_e32 v33, 0
	v_mov_b32_e32 v34, 0
	v_mov_b32_e32 v35, 0
	v_mov_b32_e32 v56, 0
	v_mov_b32_e32 v57, 0
	v_mov_b32_e32 v58, 0
	v_mov_b32_e32 v59, 0
	v_mov_b32_e32 v60, 0
	v_mov_b32_e32 v61, 0
	v_mov_b32_e32 v62, 0
	v_mov_b32_e32 v63, 0
	v_mov_b32_e32 v40, 0
	v_mov_b32_e32 v41, 0
	v_mov_b32_e32 v42, 0
	v_mov_b32_e32 v43, 0
	v_mov_b32_e32 v44, 0
	v_mov_b32_e32 v45, 0
	v_mov_b32_e32 v46, 0
	v_mov_b32_e32 v47, 0
	v_mov_b32_e32 v48, 0
	v_mov_b32_e32 v49, 0
	v_mov_b32_e32 v50, 0
	v_mov_b32_e32 v51, 0
	v_mov_b32_e32 v52, 0
	v_mov_b32_e32 v53, 0
	v_mov_b32_e32 v54, 0
	v_mov_b32_e32 v55, 0
	s_branch .LBB0_45

.LBB0_104:
	v_or_b32_e32 v86, s6, v103
	v_ashrrev_i32_e32 v87, 31, v86
	v_lshlrev_b64 v[86:87], 14, v[86:87]
	v_lshl_add_u64 v[130:131], v[46:47], 0, v[86:87]
	v_lshl_add_u64 v[142:143], v[130:131], 0, v[168:169]
	v_cndmask_b32_e64 v49, 0, 1, s[4:5]
	v_cmp_ne_u32_e32 vcc, 1, v49
	s_mov_b64 s[4:5], 0
	s_and_b64 vcc, exec, vcc
	v_lshl_add_u64 v[144:145], v[142:143], 0, s[34:35]
	v_lshl_add_u64 v[146:147], v[142:143], 0, s[26:27]
	v_lshl_add_u64 v[148:149], v[142:143], 0, s[86:87]
	global_load_dwordx4 v[176:179], v[142:143], off
	global_load_dwordx4 v[180:183], v[144:145], off
	global_load_dwordx4 v[184:187], v[146:147], off
	global_load_dwordx4 v[188:191], v[148:149], off
	global_load_dwordx4 v[192:195], v[142:143], off offset:64
	global_load_dwordx4 v[196:199], v[144:145], off offset:64
	global_load_dwordx4 v[200:203], v[146:147], off offset:64
	global_load_dwordx4 v[204:207], v[148:149], off offset:64
	global_load_dwordx4 v[222:225], v[142:143], off offset:128
	global_load_dwordx4 v[226:229], v[144:145], off offset:128
	global_load_dwordx4 v[230:233], v[146:147], off offset:128
	global_load_dwordx4 v[234:237], v[148:149], off offset:128
	global_load_dwordx4 v[238:241], v[142:143], off offset:192
	global_load_dwordx4 v[242:245], v[144:145], off offset:192
	global_load_dwordx4 v[246:249], v[146:147], off offset:192
	global_load_dwordx4 v[152:155], v[148:149], off offset:192
	s_waitcnt lgkmcnt(0)
	s_waitcnt vmcnt(15)
	v_mfma_f32_16x16x32_f16 v[106:109], v[176:179], v[0:3], 0
	v_mfma_f32_16x16x32_f16 v[110:113], v[176:179], v[8:11], 0
	s_waitcnt vmcnt(14)
	v_mfma_f32_16x16x32_f16 v[114:117], v[180:183], v[0:3], 0
	v_mfma_f32_16x16x32_f16 v[118:121], v[180:183], v[8:11], 0
	s_waitcnt vmcnt(13)
	v_mfma_f32_16x16x32_f16 v[126:129], v[184:187], v[0:3], 0
	v_mfma_f32_16x16x32_f16 v[88:91], v[184:187], v[8:11], 0
	s_waitcnt vmcnt(12)
	v_mfma_f32_16x16x32_f16 v[134:137], v[188:191], v[0:3], 0
	v_mfma_f32_16x16x32_f16 v[122:125], v[188:191], v[8:11], 0
	s_waitcnt vmcnt(11)
	v_mfma_f32_16x16x32_f16 v[106:109], v[192:195], v[4:7], v[106:109]
	v_mfma_f32_16x16x32_f16 v[110:113], v[192:195], v[12:15], v[110:113]
	s_waitcnt vmcnt(10)
	v_mfma_f32_16x16x32_f16 v[114:117], v[196:199], v[4:7], v[114:117]
	v_mfma_f32_16x16x32_f16 v[118:121], v[196:199], v[12:15], v[118:121]
	s_waitcnt vmcnt(9)
	v_mfma_f32_16x16x32_f16 v[126:129], v[200:203], v[4:7], v[126:129]
	v_mfma_f32_16x16x32_f16 v[88:91], v[200:203], v[12:15], v[88:91]
	s_waitcnt vmcnt(8)
	v_mfma_f32_16x16x32_f16 v[134:137], v[204:207], v[4:7], v[134:137]
	v_mfma_f32_16x16x32_f16 v[122:125], v[204:207], v[12:15], v[122:125]
	s_waitcnt vmcnt(7)
	v_mfma_f32_16x16x32_f16 v[106:109], v[222:225], v[16:19], v[106:109]
	v_mfma_f32_16x16x32_f16 v[110:113], v[222:225], v[24:27], v[110:113]
	s_waitcnt vmcnt(6)
	v_mfma_f32_16x16x32_f16 v[114:117], v[226:229], v[16:19], v[114:117]
	v_mfma_f32_16x16x32_f16 v[118:121], v[226:229], v[24:27], v[118:121]
	s_waitcnt vmcnt(5)
	v_mfma_f32_16x16x32_f16 v[126:129], v[230:233], v[16:19], v[126:129]
	v_mfma_f32_16x16x32_f16 v[88:91], v[230:233], v[24:27], v[88:91]
	s_waitcnt vmcnt(4)
	v_mfma_f32_16x16x32_f16 v[134:137], v[234:237], v[16:19], v[134:137]
	v_mfma_f32_16x16x32_f16 v[122:125], v[234:237], v[24:27], v[122:125]
	s_waitcnt vmcnt(3)
	v_mfma_f32_16x16x32_f16 v[106:109], v[238:241], v[20:23], v[106:109]
	v_mfma_f32_16x16x32_f16 v[110:113], v[238:241], v[28:31], v[110:113]
	s_waitcnt vmcnt(2)
	v_mfma_f32_16x16x32_f16 v[114:117], v[242:245], v[20:23], v[114:117]
	v_mfma_f32_16x16x32_f16 v[118:121], v[242:245], v[28:31], v[118:121]
	s_waitcnt vmcnt(1)
	v_mfma_f32_16x16x32_f16 v[126:129], v[246:249], v[20:23], v[126:129]
	v_mfma_f32_16x16x32_f16 v[88:91], v[246:249], v[28:31], v[88:91]
	s_waitcnt vmcnt(0)
	v_mfma_f32_16x16x32_f16 v[134:137], v[152:155], v[20:23], v[134:137]
	v_mfma_f32_16x16x32_f16 v[122:125], v[152:155], v[28:31], v[122:125]
	s_nop 7
	v_lshl_add_u32 v49, s6, 7, v104
	v_add_u32_e32 v49, 0xc400, v49
	s_mov_b32 s6, 1
	ds_read2_b32 v[86:87], v49 offset1:16
	s_waitcnt lgkmcnt(0)
	v_pk_fma_f32 v[84:85], v[106:107], v[86:87], v[84:85] op_sel_hi:[1,0,1]
	v_mov_b32_e32 v106, v87
	v_pk_fma_f32 v[68:69], v[110:111], v[106:107], v[68:69] op_sel_hi:[1,0,1]
	v_pk_fma_f32 v[82:83], v[108:109], v[86:87], v[82:83] op_sel_hi:[1,0,1]
	v_pk_fma_f32 v[66:67], v[112:113], v[106:107], v[66:67] op_sel_hi:[1,0,1]
	v_pk_fma_f32 v[80:81], v[114:115], v[86:87], v[80:81] op_sel_hi:[1,0,1]
	v_pk_fma_f32 v[64:65], v[118:119], v[106:107], v[64:65] op_sel_hi:[1,0,1]
	v_pk_fma_f32 v[78:79], v[116:117], v[86:87], v[78:79] op_sel_hi:[1,0,1]
	v_pk_fma_f32 v[62:63], v[120:121], v[106:107], v[62:63] op_sel_hi:[1,0,1]
	v_pk_fma_f32 v[76:77], v[126:127], v[86:87], v[76:77] op_sel_hi:[1,0,1]
	v_pk_fma_f32 v[60:61], v[88:89], v[106:107], v[60:61] op_sel_hi:[1,0,1]
	v_pk_fma_f32 v[74:75], v[128:129], v[86:87], v[74:75] op_sel_hi:[1,0,1]
	v_pk_fma_f32 v[58:59], v[90:91], v[106:107], v[58:59] op_sel_hi:[1,0,1]
	v_pk_fma_f32 v[72:73], v[134:135], v[86:87], v[72:73] op_sel_hi:[1,0,1]
	v_fma_f32 v70, v136, v86, v70
	v_fma_f32 v71, v137, v86, v71
	v_pk_fma_f32 v[56:57], v[122:123], v[106:107], v[56:57] op_sel_hi:[1,0,1]
	v_pk_fma_f32 v[54:55], v[124:125], v[106:107], v[54:55] op_sel_hi:[1,0,1]
	s_cbranch_vccz .LBB0_104
	v_lshl_or_b32 v2, v102, 6, v99
	v_ashrrev_i32_e32 v3, 31, v2
	v_lshlrev_b64 v[26:27], 1, v[2:3]
	v_lshlrev_b64 v[28:29], 2, v[2:3]
	v_lshl_add_u64 v[4:5], v[42:43], 0, v[26:27]
	v_lshl_add_u64 v[0:1], v[40:41], 0, v[28:29]
	global_load_dwordx2 v[8:9], v[4:5], off
	s_nop 0
	global_load_dwordx4 v[4:7], v[0:1], off
	v_lshlrev_b32_e32 v49, 1, v2
	s_waitcnt vmcnt(1)
	v_cvt_f32_f16_sdwa v3, v8 dst_sel:DWORD dst_unused:UNUSED_PAD src0_sel:WORD_1
	v_cvt_f32_f16_e32 v8, v8
	s_waitcnt vmcnt(0)
	v_pk_add_f32 v[4:5], v[84:85], v[4:5]
	v_pk_add_f32 v[6:7], v[82:83], v[6:7]
	v_mul_f32_e32 v11, 0xbfb8aa3b, v3
	v_mul_f32_e32 v10, 0xbfb8aa3b, v8
	v_exp_f32_e32 v10, v10
	v_exp_f32_e32 v11, v11
	s_nop 0
	v_pk_add_f32 v[10:11], v[10:11], 1.0 op_sel_hi:[1,0]
	s_nop 0
	v_div_scale_f32 v12, s[4:5], v11, v11, v3
	v_rcp_f32_e32 v13, v12
	s_nop 0
	v_fma_f32 v14, -v12, v13, 1.0
	v_fmac_f32_e32 v13, v14, v13
	v_div_scale_f32 v14, vcc, v3, v11, v3
	v_mul_f32_e32 v15, v14, v13
	v_fma_f32 v16, -v12, v15, v14
	v_fmac_f32_e32 v15, v16, v13
	v_fma_f32 v12, -v12, v15, v14
	v_div_fmas_f32 v12, v12, v13, v15
	v_div_fixup_f32 v11, v12, v11, v3
	v_div_scale_f32 v3, s[4:5], v10, v10, v8
	v_rcp_f32_e32 v12, v3
	s_nop 0
	v_fma_f32 v13, -v3, v12, 1.0
	v_fmac_f32_e32 v12, v13, v12
	v_div_scale_f32 v13, vcc, v8, v10, v8
	v_mul_f32_e32 v14, v13, v12
	v_fma_f32 v15, -v3, v14, v13
	v_fmac_f32_e32 v14, v15, v12
	v_fma_f32 v3, -v3, v14, v13
	v_div_fmas_f32 v3, v3, v12, v14
	v_div_fixup_f32 v10, v3, v10, v8
	v_pk_mul_f32 v[4:5], v[4:5], v[10:11]
	v_cvt_f32_f16_sdwa v3, v9 dst_sel:DWORD dst_unused:UNUSED_PAD src0_sel:WORD_1
	v_cvt_f32_f16_e32 v10, v9
	v_cvt_pk_f16_f32 v12, v4, v5
	v_mul_f32_e32 v9, 0xbfb8aa3b, v3
	v_mul_f32_e32 v8, 0xbfb8aa3b, v10
	v_exp_f32_e32 v8, v8
	v_exp_f32_e32 v9, v9
	s_nop 0
	v_pk_add_f32 v[8:9], v[8:9], 1.0 op_sel_hi:[1,0]
	s_nop 0
	v_div_scale_f32 v11, s[4:5], v9, v9, v3
	v_rcp_f32_e32 v13, v11
	s_nop 0
	v_fma_f32 v14, -v11, v13, 1.0
	v_fmac_f32_e32 v13, v14, v13
	v_div_scale_f32 v14, vcc, v3, v9, v3
	v_mul_f32_e32 v15, v14, v13
	v_fma_f32 v16, -v11, v15, v14
	v_fmac_f32_e32 v15, v16, v13
	v_fma_f32 v11, -v11, v15, v14
	v_div_fmas_f32 v11, v11, v13, v15
	v_div_fixup_f32 v9, v11, v9, v3
	v_div_scale_f32 v3, s[4:5], v8, v8, v10
	v_rcp_f32_e32 v11, v3
	s_nop 0
	v_fma_f32 v13, -v3, v11, 1.0
	v_fmac_f32_e32 v11, v13, v11
	v_div_scale_f32 v13, vcc, v10, v8, v10
	v_mul_f32_e32 v14, v13, v11
	v_fma_f32 v15, -v3, v14, v13
	v_fmac_f32_e32 v14, v15, v11
	v_fma_f32 v3, -v3, v14, v13
	v_div_fmas_f32 v3, v3, v11, v14
	v_div_fixup_f32 v8, v3, v8, v10
	v_pk_mul_f32 v[6:7], v[6:7], v[8:9]
	v_or_b32_e32 v8, 16, v2
	v_ashrrev_i32_e32 v9, 31, v8
	v_lshlrev_b64 v[22:23], 1, v[8:9]
	v_lshl_add_u64 v[8:9], v[42:43], 0, v[22:23]
	global_load_dwordx2 v[14:15], v[8:9], off
	s_nop 0
	global_load_dwordx4 v[8:11], v[0:1], off offset:64
	v_add_u32_e32 v3, v93, v49
	v_cvt_pk_f16_f32 v13, v6, v7
	v_add_u32_e32 v51, 0x4000, v3
	v_lshl_add_u64 v[22:23], v[44:45], 0, v[22:23]
	v_add_u32_e32 v49, v92, v49
	v_add_u32_e32 v49, 0x4000, v49
	s_waitcnt vmcnt(1)
	v_cvt_f32_f16_sdwa v18, v14 dst_sel:DWORD dst_unused:UNUSED_PAD src0_sel:WORD_1
	v_cvt_f32_f16_e32 v14, v14
	s_waitcnt vmcnt(0)
	v_pk_add_f32 v[8:9], v[80:81], v[8:9]
	v_pk_add_f32 v[10:11], v[78:79], v[10:11]
	v_mul_f32_e32 v17, 0xbfb8aa3b, v18
	v_mul_f32_e32 v16, 0xbfb8aa3b, v14
	v_exp_f32_e32 v16, v16
	v_exp_f32_e32 v17, v17
	s_nop 0
	v_pk_add_f32 v[16:17], v[16:17], 1.0 op_sel_hi:[1,0]
	s_nop 0
	v_div_scale_f32 v19, s[4:5], v17, v17, v18
	v_rcp_f32_e32 v20, v19
	s_nop 0
	v_fma_f32 v21, -v19, v20, 1.0
	v_fmac_f32_e32 v20, v21, v20
	v_div_scale_f32 v21, vcc, v18, v17, v18
	v_mul_f32_e32 v24, v21, v20
	v_fma_f32 v25, -v19, v24, v21
	v_fmac_f32_e32 v24, v25, v20
	v_fma_f32 v19, -v19, v24, v21
	v_div_fmas_f32 v19, v19, v20, v24
	v_div_fixup_f32 v17, v19, v17, v18
	v_div_scale_f32 v18, s[4:5], v16, v16, v14
	v_rcp_f32_e32 v19, v18
	s_nop 0
	v_fma_f32 v20, -v18, v19, 1.0
	v_fmac_f32_e32 v19, v20, v19
	v_div_scale_f32 v20, vcc, v14, v16, v14
	v_mul_f32_e32 v21, v20, v19
	v_fma_f32 v24, -v18, v21, v20
	v_fmac_f32_e32 v21, v24, v19
	v_fma_f32 v18, -v18, v21, v20
	v_div_fmas_f32 v18, v18, v19, v21
	v_div_fixup_f32 v16, v18, v16, v14
	v_cvt_f32_f16_sdwa v18, v15 dst_sel:DWORD dst_unused:UNUSED_PAD src0_sel:WORD_1
	v_cvt_f32_f16_e32 v15, v15
	v_pk_mul_f32 v[8:9], v[8:9], v[16:17]
	v_mul_f32_e32 v17, 0xbfb8aa3b, v18
	v_mul_f32_e32 v16, 0xbfb8aa3b, v15
	v_exp_f32_e32 v16, v16
	v_exp_f32_e32 v17, v17
	v_cvt_pk_f16_f32 v14, v8, v9
	v_pk_add_f32 v[16:17], v[16:17], 1.0 op_sel_hi:[1,0]
	s_nop 0
	v_div_scale_f32 v19, s[4:5], v17, v17, v18
	v_rcp_f32_e32 v20, v19
	s_nop 0
	v_fma_f32 v21, -v19, v20, 1.0
	v_fmac_f32_e32 v20, v21, v20
	v_div_scale_f32 v21, vcc, v18, v17, v18
	v_mul_f32_e32 v24, v21, v20
	v_fma_f32 v25, -v19, v24, v21
	v_fmac_f32_e32 v24, v25, v20
	v_fma_f32 v19, -v19, v24, v21
	v_div_fmas_f32 v19, v19, v20, v24
	v_div_fixup_f32 v17, v19, v17, v18
	v_div_scale_f32 v18, s[4:5], v16, v16, v15
	v_rcp_f32_e32 v19, v18
	s_nop 0
	v_fma_f32 v20, -v18, v19, 1.0
	v_fmac_f32_e32 v19, v20, v19
	v_div_scale_f32 v20, vcc, v15, v16, v15
	v_mul_f32_e32 v21, v20, v19
	v_fma_f32 v24, -v18, v21, v20
	v_fmac_f32_e32 v21, v24, v19
	v_fma_f32 v18, -v18, v21, v20
	v_div_fmas_f32 v18, v18, v19, v21
	v_div_fixup_f32 v16, v18, v16, v15
	v_pk_mul_f32 v[10:11], v[10:11], v[16:17]
	s_nop 0
	v_cvt_pk_f16_f32 v15, v10, v11
	ds_write2_b64 v51, v[12:13], v[14:15] offset0:64 offset1:68
	v_or_b32_e32 v12, 32, v2
	v_ashrrev_i32_e32 v13, 31, v12
	v_lshlrev_b64 v[20:21], 1, v[12:13]
	v_lshl_add_u64 v[12:13], v[42:43], 0, v[20:21]
	global_load_dwordx2 v[16:17], v[12:13], off
	s_nop 0
	global_load_dwordx4 v[12:15], v[0:1], off offset:128
	v_or_b32_e32 v2, 48, v2
	s_waitcnt vmcnt(1)
	v_cvt_f32_f16_sdwa v3, v16 dst_sel:DWORD dst_unused:UNUSED_PAD src0_sel:WORD_1
	v_cvt_f32_f16_e32 v16, v16
	s_waitcnt vmcnt(0)
	v_pk_add_f32 v[12:13], v[76:77], v[12:13]
	v_pk_add_f32 v[14:15], v[74:75], v[14:15]
	v_mul_f32_e32 v19, 0xbfb8aa3b, v3
	v_mul_f32_e32 v18, 0xbfb8aa3b, v16
	v_exp_f32_e32 v18, v18
	v_exp_f32_e32 v19, v19
	s_nop 0
	v_pk_add_f32 v[18:19], v[18:19], 1.0 op_sel_hi:[1,0]
	s_nop 0
	v_div_scale_f32 v24, s[4:5], v19, v19, v3
	v_rcp_f32_e32 v25, v24
	s_nop 0
	v_fma_f32 v30, -v24, v25, 1.0
	v_fmac_f32_e32 v25, v30, v25
	v_div_scale_f32 v30, vcc, v3, v19, v3
	v_mul_f32_e32 v31, v30, v25
	v_fma_f32 v53, -v24, v31, v30
	v_fmac_f32_e32 v31, v53, v25
	v_fma_f32 v24, -v24, v31, v30
	v_div_fmas_f32 v24, v24, v25, v31
	v_div_fixup_f32 v19, v24, v19, v3
	v_div_scale_f32 v3, s[4:5], v18, v18, v16
	v_rcp_f32_e32 v24, v3
	s_nop 0
	v_fma_f32 v25, -v3, v24, 1.0
	v_fmac_f32_e32 v24, v25, v24
	v_div_scale_f32 v25, vcc, v16, v18, v16
	v_mul_f32_e32 v30, v25, v24
	v_fma_f32 v31, -v3, v30, v25
	v_fmac_f32_e32 v30, v31, v24
	v_fma_f32 v3, -v3, v30, v25
	v_div_fmas_f32 v3, v3, v24, v30
	v_div_fixup_f32 v18, v3, v18, v16
	v_pk_mul_f32 v[12:13], v[12:13], v[18:19]
	v_cvt_f32_f16_sdwa v3, v17 dst_sel:DWORD dst_unused:UNUSED_PAD src0_sel:WORD_1
	v_cvt_f32_f16_e32 v18, v17
	v_cvt_pk_f16_f32 v30, v12, v13
	v_mul_f32_e32 v17, 0xbfb8aa3b, v3
	v_mul_f32_e32 v16, 0xbfb8aa3b, v18
	v_exp_f32_e32 v16, v16
	v_exp_f32_e32 v17, v17
	s_nop 0
	v_pk_add_f32 v[16:17], v[16:17], 1.0 op_sel_hi:[1,0]
	s_nop 0
	v_div_scale_f32 v19, s[4:5], v17, v17, v3
	v_rcp_f32_e32 v24, v19
	s_nop 0
	v_fma_f32 v25, -v19, v24, 1.0
	v_fmac_f32_e32 v24, v25, v24
	v_div_scale_f32 v25, vcc, v3, v17, v3
	v_mul_f32_e32 v31, v25, v24
	v_fma_f32 v53, -v19, v31, v25
	v_fmac_f32_e32 v31, v53, v24
	v_fma_f32 v19, -v19, v31, v25
	v_div_fmas_f32 v19, v19, v24, v31
	v_div_fixup_f32 v17, v19, v17, v3
	v_div_scale_f32 v3, s[4:5], v16, v16, v18
	v_rcp_f32_e32 v19, v3
	s_nop 0
	v_fma_f32 v24, -v3, v19, 1.0
	v_fmac_f32_e32 v19, v24, v19
	v_div_scale_f32 v24, vcc, v18, v16, v18
	v_mul_f32_e32 v25, v24, v19
	v_fma_f32 v31, -v3, v25, v24
	v_fmac_f32_e32 v25, v31, v19
	v_fma_f32 v3, -v3, v25, v24
	v_div_fmas_f32 v3, v3, v19, v25
	v_div_fixup_f32 v16, v3, v16, v18
	v_ashrrev_i32_e32 v3, 31, v2
	v_lshlrev_b64 v[24:25], 1, v[2:3]
	v_lshl_add_u64 v[2:3], v[42:43], 0, v[24:25]
	global_load_dwordx2 v[18:19], v[2:3], off
	s_nop 0
	global_load_dwordx4 v[0:3], v[0:1], off offset:192
	v_pk_mul_f32 v[14:15], v[14:15], v[16:17]
	s_waitcnt vmcnt(1)
	v_cvt_f32_f16_sdwa v53, v18 dst_sel:DWORD dst_unused:UNUSED_PAD src0_sel:WORD_1
	v_cvt_f32_f16_e32 v18, v18
	s_waitcnt vmcnt(0)
	v_pk_add_f32 v[0:1], v[72:73], v[0:1]
	v_pk_add_f32 v[2:3], v[70:71], v[2:3]
	v_mul_f32_e32 v17, 0xbfb8aa3b, v53
	v_mul_f32_e32 v16, 0xbfb8aa3b, v18
	v_exp_f32_e32 v16, v16
	v_exp_f32_e32 v17, v17
	v_cvt_pk_f16_f32 v31, v14, v15
	v_pk_add_f32 v[16:17], v[16:17], 1.0 op_sel_hi:[1,0]
	s_nop 0
	v_div_scale_f32 v72, s[4:5], v17, v17, v53
	v_rcp_f32_e32 v73, v72
	s_nop 0
	v_fma_f32 v74, -v72, v73, 1.0
	v_fmac_f32_e32 v73, v74, v73
	v_div_scale_f32 v74, vcc, v53, v17, v53
	v_mul_f32_e32 v75, v74, v73
	v_fma_f32 v76, -v72, v75, v74
	v_fmac_f32_e32 v75, v76, v73
	v_fma_f32 v72, -v72, v75, v74
	v_div_fmas_f32 v72, v72, v73, v75
	v_div_fixup_f32 v17, v72, v17, v53
	v_div_scale_f32 v53, s[4:5], v16, v16, v18
	v_rcp_f32_e32 v72, v53
	s_nop 0
	v_fma_f32 v73, -v53, v72, 1.0
	v_fmac_f32_e32 v72, v73, v72
	v_div_scale_f32 v73, vcc, v18, v16, v18
	v_mul_f32_e32 v74, v73, v72
	v_fma_f32 v75, -v53, v74, v73
	v_fmac_f32_e32 v74, v75, v72
	v_fma_f32 v53, -v53, v74, v73
	v_div_fmas_f32 v53, v53, v72, v74
	v_div_fixup_f32 v16, v53, v16, v18
	v_pk_mul_f32 v[16:17], v[0:1], v[16:17]
	v_cvt_f32_f16_sdwa v1, v19 dst_sel:DWORD dst_unused:UNUSED_PAD src0_sel:WORD_1
	v_cvt_f32_f16_e32 v53, v19
	v_cvt_pk_f16_f32 v0, v16, v17
	v_mul_f32_e32 v19, 0xbfb8aa3b, v1
	v_mul_f32_e32 v18, 0xbfb8aa3b, v53
	v_exp_f32_e32 v18, v18
	v_exp_f32_e32 v19, v19
	s_nop 0
	v_pk_add_f32 v[18:19], v[18:19], 1.0 op_sel_hi:[1,0]
	s_nop 0
	v_div_scale_f32 v70, s[4:5], v19, v19, v1
	v_rcp_f32_e32 v71, v70
	s_nop 0
	v_fma_f32 v72, -v70, v71, 1.0
	v_fmac_f32_e32 v71, v72, v71
	v_div_scale_f32 v72, vcc, v1, v19, v1
	v_mul_f32_e32 v73, v72, v71
	v_fma_f32 v74, -v70, v73, v72
	v_fmac_f32_e32 v73, v74, v71
	v_fma_f32 v70, -v70, v73, v72
	v_div_fmas_f32 v70, v70, v71, v73
	v_div_fixup_f32 v19, v70, v19, v1
	v_div_scale_f32 v1, s[4:5], v18, v18, v53
	v_rcp_f32_e32 v70, v1
	s_nop 0
	v_fma_f32 v71, -v1, v70, 1.0
	v_fmac_f32_e32 v70, v71, v70
	v_div_scale_f32 v71, vcc, v53, v18, v53
	v_mul_f32_e32 v72, v71, v70
	v_fma_f32 v73, -v1, v72, v71
	v_fmac_f32_e32 v72, v73, v70
	v_fma_f32 v1, -v1, v72, v71
	v_div_fmas_f32 v1, v1, v70, v72
	v_div_fixup_f32 v18, v1, v18, v53
	v_pk_mul_f32 v[18:19], v[2:3], v[18:19]
	v_lshl_add_u64 v[2:3], v[44:45], 0, v[26:27]
	v_cvt_pk_f16_f32 v1, v18, v19
	ds_write2_b64 v51, v[30:31], v[0:1] offset0:72 offset1:76
	v_lshl_add_u64 v[0:1], v[38:39], 0, v[28:29]
	global_load_dwordx2 v[2:3], v[2:3], off
	s_nop 0
	global_load_dwordx4 v[26:29], v[0:1], off
	s_waitcnt vmcnt(1)
	v_cvt_f32_f16_sdwa v51, v2 dst_sel:DWORD dst_unused:UNUSED_PAD src0_sel:WORD_1
	v_cvt_f32_f16_e32 v2, v2
	s_waitcnt vmcnt(0)
	v_pk_add_f32 v[26:27], v[68:69], v[26:27]
	v_pk_add_f32 v[28:29], v[66:67], v[28:29]
	v_mul_f32_e32 v31, 0xbfb8aa3b, v51
	v_mul_f32_e32 v30, 0xbfb8aa3b, v2
	v_exp_f32_e32 v30, v30
	v_exp_f32_e32 v31, v31
	s_nop 0
	v_pk_add_f32 v[30:31], v[30:31], 1.0 op_sel_hi:[1,0]
	s_nop 0
	v_div_scale_f32 v53, s[4:5], v31, v31, v51
	v_rcp_f32_e32 v68, v53
	s_nop 0
	v_fma_f32 v69, -v53, v68, 1.0
	v_fmac_f32_e32 v68, v69, v68
	v_div_scale_f32 v69, vcc, v51, v31, v51
	v_mul_f32_e32 v70, v69, v68
	v_fma_f32 v71, -v53, v70, v69
	v_fmac_f32_e32 v70, v71, v68
	v_fma_f32 v53, -v53, v70, v69
	v_div_fmas_f32 v53, v53, v68, v70
	v_div_fixup_f32 v31, v53, v31, v51
	v_div_scale_f32 v51, s[4:5], v30, v30, v2
	v_rcp_f32_e32 v53, v51
	s_nop 0
	v_fma_f32 v68, -v51, v53, 1.0
	v_fmac_f32_e32 v53, v68, v53
	v_div_scale_f32 v68, vcc, v2, v30, v2
	v_mul_f32_e32 v69, v68, v53
	v_fma_f32 v70, -v51, v69, v68
	v_fmac_f32_e32 v69, v70, v53
	v_fma_f32 v51, -v51, v69, v68
	v_div_fmas_f32 v51, v51, v53, v69
	v_div_fixup_f32 v30, v51, v30, v2
	v_cvt_f32_f16_sdwa v51, v3 dst_sel:DWORD dst_unused:UNUSED_PAD src0_sel:WORD_1
	v_cvt_f32_f16_e32 v3, v3
	v_pk_mul_f32 v[26:27], v[26:27], v[30:31]
	v_mul_f32_e32 v31, 0xbfb8aa3b, v51
	v_mul_f32_e32 v30, 0xbfb8aa3b, v3
	v_exp_f32_e32 v30, v30
	v_exp_f32_e32 v31, v31
	v_cvt_pk_f16_f32 v2, v26, v27
	v_pk_add_f32 v[30:31], v[30:31], 1.0 op_sel_hi:[1,0]
	s_nop 0
	v_div_scale_f32 v53, s[4:5], v31, v31, v51
	v_rcp_f32_e32 v66, v53
	s_nop 0
	v_fma_f32 v67, -v53, v66, 1.0
	v_fmac_f32_e32 v66, v67, v66
	v_div_scale_f32 v67, vcc, v51, v31, v51
	v_mul_f32_e32 v68, v67, v66
	v_fma_f32 v69, -v53, v68, v67
	v_fmac_f32_e32 v68, v69, v66
	v_fma_f32 v53, -v53, v68, v67
	v_div_fmas_f32 v53, v53, v66, v68
	v_div_fixup_f32 v31, v53, v31, v51
	v_div_scale_f32 v51, s[4:5], v30, v30, v3
	v_rcp_f32_e32 v53, v51
	s_nop 0
	v_fma_f32 v66, -v51, v53, 1.0
	v_fmac_f32_e32 v53, v66, v53
	v_div_scale_f32 v66, vcc, v3, v30, v3
	v_mul_f32_e32 v67, v66, v53
	v_fma_f32 v68, -v51, v67, v66
	v_fmac_f32_e32 v67, v68, v53
	v_fma_f32 v51, -v51, v67, v66
	v_div_fmas_f32 v51, v51, v53, v67
	v_div_fixup_f32 v30, v51, v30, v3
	v_pk_mul_f32 v[28:29], v[28:29], v[30:31]
	global_load_dwordx2 v[30:31], v[22:23], off
	global_load_dwordx4 v[66:69], v[0:1], off offset:64
	v_cvt_pk_f16_f32 v3, v28, v29
	s_waitcnt vmcnt(1)
	v_cvt_f32_f16_sdwa v51, v30 dst_sel:DWORD dst_unused:UNUSED_PAD src0_sel:WORD_1
	v_cvt_f32_f16_e32 v30, v30
	s_waitcnt vmcnt(0)
	v_pk_add_f32 v[22:23], v[64:65], v[66:67]
	v_pk_add_f32 v[62:63], v[62:63], v[68:69]
	v_mul_f32_e32 v53, 0xbfb8aa3b, v30
	v_exp_f32_e32 v64, v53
	v_mul_f32_e32 v53, 0xbfb8aa3b, v51
	v_exp_f32_e32 v65, v53
	s_nop 0
	v_pk_add_f32 v[64:65], v[64:65], 1.0 op_sel_hi:[1,0]
	s_nop 0
	v_div_scale_f32 v53, s[4:5], v65, v65, v51
	v_rcp_f32_e32 v66, v53
	s_nop 0
	v_fma_f32 v67, -v53, v66, 1.0
	v_fmac_f32_e32 v66, v67, v66
	v_div_scale_f32 v67, vcc, v51, v65, v51
	v_mul_f32_e32 v70, v67, v66
	v_fma_f32 v71, -v53, v70, v67
	v_fmac_f32_e32 v70, v71, v66
	v_fma_f32 v53, -v53, v70, v67
	v_div_fmas_f32 v53, v53, v66, v70
	v_div_fixup_f32 v65, v53, v65, v51
	v_div_scale_f32 v51, s[4:5], v64, v64, v30
	v_rcp_f32_e32 v53, v51
	s_nop 0
	v_fma_f32 v66, -v51, v53, 1.0
	v_fmac_f32_e32 v53, v66, v53
	v_div_scale_f32 v66, vcc, v30, v64, v30
	v_mul_f32_e32 v67, v66, v53
	v_fma_f32 v70, -v51, v67, v66
	v_fmac_f32_e32 v67, v70, v53
	v_fma_f32 v51, -v51, v67, v66
	v_div_fmas_f32 v51, v51, v53, v67
	v_div_fixup_f32 v64, v51, v64, v30
	v_cvt_f32_f16_sdwa v51, v31 dst_sel:DWORD dst_unused:UNUSED_PAD src0_sel:WORD_1
	v_cvt_f32_f16_e32 v53, v31
	v_pk_mul_f32 v[22:23], v[22:23], v[64:65]
	v_mul_f32_e32 v31, 0xbfb8aa3b, v51
	v_mul_f32_e32 v30, 0xbfb8aa3b, v53
	v_exp_f32_e32 v30, v30
	v_exp_f32_e32 v31, v31
	v_cvt_pk_f16_f32 v64, v22, v23
	v_pk_add_f32 v[30:31], v[30:31], 1.0 op_sel_hi:[1,0]
	s_nop 0
	v_div_scale_f32 v65, s[4:5], v31, v31, v51
	v_rcp_f32_e32 v66, v65
	s_nop 0
	v_fma_f32 v67, -v65, v66, 1.0
	v_fmac_f32_e32 v66, v67, v66
	v_div_scale_f32 v67, vcc, v51, v31, v51
	v_mul_f32_e32 v68, v67, v66
	v_fma_f32 v69, -v65, v68, v67
	v_fmac_f32_e32 v68, v69, v66
	v_fma_f32 v65, -v65, v68, v67
	v_div_fmas_f32 v65, v65, v66, v68
	v_div_fixup_f32 v31, v65, v31, v51
	v_div_scale_f32 v51, s[4:5], v30, v30, v53
	v_rcp_f32_e32 v65, v51
	s_nop 0
	v_fma_f32 v66, -v51, v65, 1.0
	v_fmac_f32_e32 v65, v66, v65
	v_div_scale_f32 v66, vcc, v53, v30, v53
	v_mul_f32_e32 v67, v66, v65
	v_fma_f32 v68, -v51, v67, v66
	v_fmac_f32_e32 v67, v68, v65
	v_fma_f32 v51, -v51, v67, v66
	v_div_fmas_f32 v51, v51, v65, v67
	v_div_fixup_f32 v30, v51, v30, v53
	v_pk_mul_f32 v[30:31], v[62:63], v[30:31]
	s_nop 0
	v_cvt_pk_f16_f32 v65, v30, v31
	ds_write2_b64 v49, v[2:3], v[64:65] offset0:64 offset1:68
	v_lshl_add_u64 v[2:3], v[44:45], 0, v[20:21]
	global_load_dwordx2 v[2:3], v[2:3], off
	s_nop 0
	global_load_dwordx4 v[62:65], v[0:1], off offset:128
	s_waitcnt vmcnt(1)
	v_cvt_f32_f16_sdwa v51, v2 dst_sel:DWORD dst_unused:UNUSED_PAD src0_sel:WORD_1
	v_cvt_f32_f16_e32 v2, v2
	s_waitcnt vmcnt(0)
	v_pk_add_f32 v[20:21], v[60:61], v[62:63]
	v_pk_add_f32 v[58:59], v[58:59], v[64:65]
	v_mul_f32_e32 v53, 0xbfb8aa3b, v2
	v_exp_f32_e32 v60, v53
	v_mul_f32_e32 v53, 0xbfb8aa3b, v51
	v_exp_f32_e32 v61, v53
	s_nop 0
	v_pk_add_f32 v[60:61], v[60:61], 1.0 op_sel_hi:[1,0]
	s_nop 0
	v_div_scale_f32 v53, s[4:5], v61, v61, v51
	v_rcp_f32_e32 v62, v53
	s_nop 0
	v_fma_f32 v63, -v53, v62, 1.0
	v_fmac_f32_e32 v62, v63, v62
	v_div_scale_f32 v63, vcc, v51, v61, v51
	v_mul_f32_e32 v66, v63, v62
	v_fma_f32 v67, -v53, v66, v63
	v_fmac_f32_e32 v66, v67, v62
	v_fma_f32 v53, -v53, v66, v63
	v_div_fmas_f32 v53, v53, v62, v66
	v_div_fixup_f32 v61, v53, v61, v51
	v_div_scale_f32 v51, s[4:5], v60, v60, v2
	v_rcp_f32_e32 v53, v51
	s_nop 0
	v_fma_f32 v62, -v51, v53, 1.0
	v_fmac_f32_e32 v53, v62, v53
	v_div_scale_f32 v62, vcc, v2, v60, v2
	v_mul_f32_e32 v63, v62, v53
	v_fma_f32 v66, -v51, v63, v62
	v_fmac_f32_e32 v63, v66, v53
	v_fma_f32 v51, -v51, v63, v62
	v_div_fmas_f32 v51, v51, v53, v63
	v_div_fixup_f32 v60, v51, v60, v2
	v_pk_mul_f32 v[60:61], v[20:21], v[60:61]
	v_cvt_f32_f16_sdwa v21, v3 dst_sel:DWORD dst_unused:UNUSED_PAD src0_sel:WORD_1
	v_cvt_f32_f16_e32 v51, v3
	v_cvt_pk_f16_f32 v20, v60, v61
	v_mul_f32_e32 v3, 0xbfb8aa3b, v21
	v_mul_f32_e32 v2, 0xbfb8aa3b, v51
	v_exp_f32_e32 v2, v2
	v_exp_f32_e32 v3, v3
	s_nop 0
	v_pk_add_f32 v[2:3], v[2:3], 1.0 op_sel_hi:[1,0]
	s_nop 0
	v_div_scale_f32 v53, s[4:5], v3, v3, v21
	v_rcp_f32_e32 v62, v53
	s_nop 0
	v_fma_f32 v63, -v53, v62, 1.0
	v_fmac_f32_e32 v62, v63, v62
	v_div_scale_f32 v63, vcc, v21, v3, v21
	v_mul_f32_e32 v64, v63, v62
	v_fma_f32 v65, -v53, v64, v63
	v_fmac_f32_e32 v64, v65, v62
	v_fma_f32 v53, -v53, v64, v63
	v_div_fmas_f32 v53, v53, v62, v64
	v_div_fixup_f32 v3, v53, v3, v21
	v_div_scale_f32 v21, s[4:5], v2, v2, v51
	v_rcp_f32_e32 v53, v21
	s_nop 0
	v_fma_f32 v62, -v21, v53, 1.0
	v_fmac_f32_e32 v53, v62, v53
	v_div_scale_f32 v62, vcc, v51, v2, v51
	v_mul_f32_e32 v63, v62, v53
	v_fma_f32 v64, -v21, v63, v62
	v_fmac_f32_e32 v63, v64, v53
	v_fma_f32 v21, -v21, v63, v62
	v_div_fmas_f32 v21, v21, v53, v63
	v_div_fixup_f32 v2, v21, v2, v51
	v_pk_mul_f32 v[58:59], v[58:59], v[2:3]
	v_lshl_add_u64 v[2:3], v[44:45], 0, v[24:25]
	global_load_dwordx2 v[24:25], v[2:3], off
	s_nop 0
	global_load_dwordx4 v[0:3], v[0:1], off offset:192
	v_cvt_pk_f16_f32 v21, v58, v59
	s_waitcnt vmcnt(1)
	v_cvt_f32_f16_sdwa v51, v24 dst_sel:DWORD dst_unused:UNUSED_PAD src0_sel:WORD_1
	v_cvt_f32_f16_e32 v24, v24
	s_waitcnt vmcnt(0)
	v_pk_add_f32 v[0:1], v[56:57], v[0:1]
	v_pk_add_f32 v[2:3], v[54:55], v[2:3]
	v_mul_f32_e32 v53, 0xbfb8aa3b, v24
	v_exp_f32_e32 v56, v53
	v_mul_f32_e32 v53, 0xbfb8aa3b, v51
	v_exp_f32_e32 v57, v53
	s_nop 0
	v_pk_add_f32 v[56:57], v[56:57], 1.0 op_sel_hi:[1,0]
	s_nop 0
	v_div_scale_f32 v53, s[4:5], v57, v57, v51
	v_rcp_f32_e32 v62, v53
	s_nop 0
	v_fma_f32 v63, -v53, v62, 1.0
	v_fmac_f32_e32 v62, v63, v62
	v_div_scale_f32 v63, vcc, v51, v57, v51
	v_mul_f32_e32 v64, v63, v62
	v_fma_f32 v65, -v53, v64, v63
	v_fmac_f32_e32 v64, v65, v62
	v_fma_f32 v53, -v53, v64, v63
	v_div_fmas_f32 v53, v53, v62, v64
	v_div_fixup_f32 v57, v53, v57, v51
	v_div_scale_f32 v51, s[4:5], v56, v56, v24
	v_rcp_f32_e32 v53, v51
	s_nop 0
	v_fma_f32 v62, -v51, v53, 1.0
	v_fmac_f32_e32 v53, v62, v53
	v_div_scale_f32 v62, vcc, v24, v56, v24
	v_mul_f32_e32 v63, v62, v53
	v_fma_f32 v64, -v51, v63, v62
	v_fmac_f32_e32 v63, v64, v53
	v_fma_f32 v51, -v51, v63, v62
	v_div_fmas_f32 v51, v51, v53, v63
	v_div_fixup_f32 v56, v51, v56, v24
	v_cvt_f32_f16_sdwa v51, v25 dst_sel:DWORD dst_unused:UNUSED_PAD src0_sel:WORD_1
	v_cvt_f32_f16_e32 v25, v25
	v_pk_mul_f32 v[0:1], v[0:1], v[56:57]
	v_mul_f32_e32 v53, 0xbfb8aa3b, v25
	v_exp_f32_e32 v54, v53
	v_mul_f32_e32 v53, 0xbfb8aa3b, v51
	v_exp_f32_e32 v55, v53
	v_cvt_pk_f16_f32 v24, v0, v1
	v_pk_add_f32 v[54:55], v[54:55], 1.0 op_sel_hi:[1,0]
	s_nop 0
	v_div_scale_f32 v53, s[4:5], v55, v55, v51
	v_rcp_f32_e32 v56, v53
	s_nop 0
	v_fma_f32 v57, -v53, v56, 1.0
	v_fmac_f32_e32 v56, v57, v56
	v_div_scale_f32 v57, vcc, v51, v55, v51
	v_mul_f32_e32 v62, v57, v56
	v_fma_f32 v63, -v53, v62, v57
	v_fmac_f32_e32 v62, v63, v56
	v_fma_f32 v53, -v53, v62, v57
	v_div_fmas_f32 v53, v53, v56, v62
	v_div_fixup_f32 v55, v53, v55, v51
	v_div_scale_f32 v51, s[4:5], v54, v54, v25
	v_rcp_f32_e32 v53, v51
	s_mov_b64 s[4:5], 0
	v_fma_f32 v56, -v51, v53, 1.0
	v_fmac_f32_e32 v53, v56, v53
	v_div_scale_f32 v56, vcc, v25, v54, v25
	v_mul_f32_e32 v57, v56, v53
	v_fma_f32 v62, -v51, v57, v56
	v_fmac_f32_e32 v57, v62, v53
	v_fma_f32 v51, -v51, v57, v56
	v_div_fmas_f32 v51, v51, v53, v57
	v_div_fixup_f32 v54, v51, v54, v25
	v_pk_mul_f32 v[2:3], v[2:3], v[54:55]
	v_mov_b32_e32 v55, v4
	v_mov_b32_e32 v4, v27
	v_mov_b32_e32 v54, v26
	v_pk_mul_f32 v[4:5], v[4:5], v[4:5]
	v_mov_b32_e32 v26, v28
	v_pk_fma_f32 v[4:5], v[54:55], v[54:55], v[4:5]
	v_mov_b32_e32 v27, v6
	v_mov_b32_e32 v6, v29
	v_pk_fma_f32 v[4:5], v[26:27], v[26:27], v[4:5]
	v_cvt_pk_f16_f32 v25, v2, v3
	v_pk_fma_f32 v[4:5], v[6:7], v[6:7], v[4:5]
	v_mov_b32_e32 v7, v8
	v_mov_b32_e32 v8, v23
	v_mov_b32_e32 v6, v22
	v_pk_mul_f32 v[8:9], v[8:9], v[8:9]
	v_pk_add_f32 v[4:5], v[36:37], v[4:5]
	v_pk_fma_f32 v[6:7], v[6:7], v[6:7], v[8:9]
	v_mov_b32_e32 v8, v30
	v_mov_b32_e32 v9, v10
	v_mov_b32_e32 v10, v31
	v_pk_fma_f32 v[6:7], v[8:9], v[8:9], v[6:7]
	s_and_b64 vcc, exec, s[36:37]
	v_pk_fma_f32 v[6:7], v[10:11], v[10:11], v[6:7]
	ds_write2_b64 v49, v[20:21], v[24:25] offset0:72 offset1:76
	v_pk_add_f32 v[4:5], v[4:5], v[6:7]
	v_mov_b32_e32 v7, v12
	v_mov_b32_e32 v12, v61
	v_mov_b32_e32 v6, v60
	v_pk_mul_f32 v[8:9], v[12:13], v[12:13]
	s_nop 0
	v_pk_fma_f32 v[6:7], v[6:7], v[6:7], v[8:9]
	v_mov_b32_e32 v8, v58
	v_mov_b32_e32 v9, v14
	v_mov_b32_e32 v14, v59
	v_pk_fma_f32 v[6:7], v[8:9], v[8:9], v[6:7]
	s_nop 0
	v_pk_fma_f32 v[6:7], v[14:15], v[14:15], v[6:7]
	s_nop 0
	v_pk_add_f32 v[4:5], v[4:5], v[6:7]
	v_mov_b32_e32 v7, v16
	v_mov_b32_e32 v16, v1
	v_mov_b32_e32 v6, v0
	v_pk_mul_f32 v[0:1], v[16:17], v[16:17]
	s_nop 0
	v_pk_fma_f32 v[0:1], v[6:7], v[6:7], v[0:1]
	v_mov_b32_e32 v6, v2
	v_mov_b32_e32 v7, v18
	v_mov_b32_e32 v18, v3
	v_pk_fma_f32 v[0:1], v[6:7], v[6:7], v[0:1]
	s_nop 0
	v_pk_fma_f32 v[0:1], v[18:19], v[18:19], v[0:1]
	s_nop 0
	v_pk_add_f32 v[36:37], v[4:5], v[0:1]
	s_cbranch_vccz .LBB0_103
	v_mbcnt_hi_u32_b32 v0, -1, v214
	v_and_b32_e32 v2, 64, v0
	v_xor_b32_e32 v1, 16, v0
	v_add_u32_e32 v3, 64, v2
	v_cmp_lt_i32_e32 vcc, v1, v3
	s_nop 1
	v_cndmask_b32_e32 v1, v0, v1, vcc
	v_lshlrev_b32_e32 v2, 2, v1
	ds_bpermute_b32 v4, v2, v37
	v_xor_b32_e32 v1, 32, v0
	v_cmp_lt_i32_e32 vcc, v1, v3
	s_waitcnt lgkmcnt(0)
	v_add_f32_e32 v4, v37, v4
	v_cndmask_b32_e32 v0, v0, v1, vcc
	v_lshlrev_b32_e32 v3, 2, v0
	ds_bpermute_b32 v5, v3, v4
	v_lshlrev_b32_e32 v0, 7, v95
	v_cmp_eq_u32_e32 vcc, 0, v96
	v_lshl_or_b32 v1, v94, 2, v0
	s_and_saveexec_b64 s[4:5], vcc
	s_cbranch_execz .LBB0_108
	s_waitcnt lgkmcnt(0)
	v_add_f32_e32 v4, v4, v5
	ds_write_b32 v1, v4 offset:52224
